# prep_mod silu prologue with batched loads (2 scalar + 12 vector loads in flight instead of 12 dependent round trips), now on phase 0's critical path after the rope split
# speedup vs baseline: 1.0086x; 1.0046x over previous
.LBB0_1142:
	v_mbcnt_lo_u32_b32 v0, -1, 0
	v_mbcnt_hi_u32_b32 v0, -1, v0
	s_mov_b64 s[4:5], 0
	v_add_u32_e32 v38, s48, v0
	s_nop 0
	v_and_b32_e32 v39, 0xff, v38
	v_lshlrev_b32_e32 v40, 2, v39
	v_add_u32_e32 v0, s33, v40
	v_mov_b32_e32 v1, v39
	s_load_dwordx2 s[2:3], s[54:55], 0x8
	s_load_dwordx2 s[6:7], s[54:55], 0x18
	s_mov_b32 s22, 0x42ce8ed0
	s_mov_b32 s23, 0xc2b17218
	v_add_u32_e32 v21, 0x1000, v40
	s_waitcnt lgkmcnt(0)
	global_load_dword v2, v40, s[2:3]
	global_load_dword v3, v40, s[2:3] offset:1024
	global_load_dword v4, v40, s[2:3] offset:2048
	global_load_dword v5, v40, s[2:3] offset:3072
	global_load_dword v6, v21, s[2:3]
	global_load_dword v7, v21, s[2:3] offset:1024
	global_load_dword v8, v21, s[2:3] offset:2048
	global_load_dword v9, v21, s[2:3] offset:3072
	global_load_dword v10, v40, s[6:7]
	global_load_dword v11, v40, s[6:7] offset:1024
	global_load_dword v12, v40, s[6:7] offset:2048
	global_load_dword v13, v40, s[6:7] offset:3072
	s_waitcnt vmcnt(11)
	v_mul_f32_e32 v14, 0xbfb8aa3b, v2
	v_fma_f32 v15, v2, s30, -v14
	v_rndne_f32_e32 v16, v14
	v_fmac_f32_e32 v15, 0xb2a5705f, v2
	v_sub_f32_e32 v14, v14, v16
	v_add_f32_e32 v14, v14, v15
	v_cvt_i32_f32_e32 v16, v16
	v_exp_f32_e32 v14, v14
	v_cmp_nlt_f32_e32 vcc, s22, v2
	s_nop 0
	v_ldexp_f32 v14, v14, v16
	v_cndmask_b32_e32 v14, 0, v14, vcc
	v_cmp_ngt_f32_e32 vcc, s23, v2
	s_nop 1
	v_cndmask_b32_e32 v14, v162, v14, vcc
	v_add_f32_e32 v14, 1.0, v14
	v_div_scale_f32 v15, s[8:9], v14, v14, v2
	v_rcp_f32_e32 v16, v15
	v_div_scale_f32 v17, vcc, v2, v14, v2
	v_fma_f32 v18, -v15, v16, 1.0
	v_fmac_f32_e32 v16, v18, v16
	v_mul_f32_e32 v18, v17, v16
	v_fma_f32 v19, -v15, v18, v17
	v_fmac_f32_e32 v18, v19, v16
	v_fma_f32 v15, -v15, v18, v17
	v_div_fmas_f32 v15, v15, v16, v18
	v_div_fixup_f32 v2, v15, v14, v2
	ds_write_b32 v0, v2
	s_waitcnt vmcnt(10)
	v_mul_f32_e32 v14, 0xbfb8aa3b, v3
	v_fma_f32 v15, v3, s30, -v14
	v_rndne_f32_e32 v16, v14
	v_fmac_f32_e32 v15, 0xb2a5705f, v3
	v_sub_f32_e32 v14, v14, v16
	v_add_f32_e32 v14, v14, v15
	v_cvt_i32_f32_e32 v16, v16
	v_exp_f32_e32 v14, v14
	v_cmp_nlt_f32_e32 vcc, s22, v3
	s_nop 0
	v_ldexp_f32 v14, v14, v16
	v_cndmask_b32_e32 v14, 0, v14, vcc
	v_cmp_ngt_f32_e32 vcc, s23, v3
	s_nop 1
	v_cndmask_b32_e32 v14, v162, v14, vcc
	v_add_f32_e32 v14, 1.0, v14
	v_div_scale_f32 v15, s[8:9], v14, v14, v3
	v_rcp_f32_e32 v16, v15
	v_div_scale_f32 v17, vcc, v3, v14, v3
	v_fma_f32 v18, -v15, v16, 1.0
	v_fmac_f32_e32 v16, v18, v16
	v_mul_f32_e32 v18, v17, v16
	v_fma_f32 v19, -v15, v18, v17
	v_fmac_f32_e32 v18, v19, v16
	v_fma_f32 v15, -v15, v18, v17
	v_div_fmas_f32 v15, v15, v16, v18
	v_div_fixup_f32 v3, v15, v14, v3
	ds_write_b32 v0, v3 offset:1024
	s_waitcnt vmcnt(9)
	v_mul_f32_e32 v14, 0xbfb8aa3b, v4
	v_fma_f32 v15, v4, s30, -v14
	v_rndne_f32_e32 v16, v14
	v_fmac_f32_e32 v15, 0xb2a5705f, v4
	v_sub_f32_e32 v14, v14, v16
	v_add_f32_e32 v14, v14, v15
	v_cvt_i32_f32_e32 v16, v16
	v_exp_f32_e32 v14, v14
	v_cmp_nlt_f32_e32 vcc, s22, v4
	s_nop 0
	v_ldexp_f32 v14, v14, v16
	v_cndmask_b32_e32 v14, 0, v14, vcc
	v_cmp_ngt_f32_e32 vcc, s23, v4
	s_nop 1
	v_cndmask_b32_e32 v14, v162, v14, vcc
	v_add_f32_e32 v14, 1.0, v14
	v_div_scale_f32 v15, s[8:9], v14, v14, v4
	v_rcp_f32_e32 v16, v15
	v_div_scale_f32 v17, vcc, v4, v14, v4
	v_fma_f32 v18, -v15, v16, 1.0
	v_fmac_f32_e32 v16, v18, v16
	v_mul_f32_e32 v18, v17, v16
	v_fma_f32 v19, -v15, v18, v17
	v_fmac_f32_e32 v18, v19, v16
	v_fma_f32 v15, -v15, v18, v17
	v_div_fmas_f32 v15, v15, v16, v18
	v_div_fixup_f32 v4, v15, v14, v4
	ds_write_b32 v0, v4 offset:2048
	s_waitcnt vmcnt(8)
	v_mul_f32_e32 v14, 0xbfb8aa3b, v5
	v_fma_f32 v15, v5, s30, -v14
	v_rndne_f32_e32 v16, v14
	v_fmac_f32_e32 v15, 0xb2a5705f, v5
	v_sub_f32_e32 v14, v14, v16
	v_add_f32_e32 v14, v14, v15
	v_cvt_i32_f32_e32 v16, v16
	v_exp_f32_e32 v14, v14
	v_cmp_nlt_f32_e32 vcc, s22, v5
	s_nop 0
	v_ldexp_f32 v14, v14, v16
	v_cndmask_b32_e32 v14, 0, v14, vcc
	v_cmp_ngt_f32_e32 vcc, s23, v5
	s_nop 1
	v_cndmask_b32_e32 v14, v162, v14, vcc
	v_add_f32_e32 v14, 1.0, v14
	v_div_scale_f32 v15, s[8:9], v14, v14, v5
	v_rcp_f32_e32 v16, v15
	v_div_scale_f32 v17, vcc, v5, v14, v5
	v_fma_f32 v18, -v15, v16, 1.0
	v_fmac_f32_e32 v16, v18, v16
	v_mul_f32_e32 v18, v17, v16
	v_fma_f32 v19, -v15, v18, v17
	v_fmac_f32_e32 v18, v19, v16
	v_fma_f32 v15, -v15, v18, v17
	v_div_fmas_f32 v15, v15, v16, v18
	v_div_fixup_f32 v5, v15, v14, v5
	ds_write_b32 v0, v5 offset:3072
	s_waitcnt vmcnt(7)
	v_mul_f32_e32 v14, 0xbfb8aa3b, v6
	v_fma_f32 v15, v6, s30, -v14
	v_rndne_f32_e32 v16, v14
	v_fmac_f32_e32 v15, 0xb2a5705f, v6
	v_sub_f32_e32 v14, v14, v16
	v_add_f32_e32 v14, v14, v15
	v_cvt_i32_f32_e32 v16, v16
	v_exp_f32_e32 v14, v14
	v_cmp_nlt_f32_e32 vcc, s22, v6
	s_nop 0
	v_ldexp_f32 v14, v14, v16
	v_cndmask_b32_e32 v14, 0, v14, vcc
	v_cmp_ngt_f32_e32 vcc, s23, v6
	s_nop 1
	v_cndmask_b32_e32 v14, v162, v14, vcc
	v_add_f32_e32 v14, 1.0, v14
	v_div_scale_f32 v15, s[8:9], v14, v14, v6
	v_rcp_f32_e32 v16, v15
	v_div_scale_f32 v17, vcc, v6, v14, v6
	v_fma_f32 v18, -v15, v16, 1.0
	v_fmac_f32_e32 v16, v18, v16
	v_mul_f32_e32 v18, v17, v16
	v_fma_f32 v19, -v15, v18, v17
	v_fmac_f32_e32 v18, v19, v16
	v_fma_f32 v15, -v15, v18, v17
	v_div_fmas_f32 v15, v15, v16, v18
	v_div_fixup_f32 v6, v15, v14, v6
	ds_write_b32 v0, v6 offset:4096
	s_waitcnt vmcnt(6)
	v_mul_f32_e32 v14, 0xbfb8aa3b, v7
	v_fma_f32 v15, v7, s30, -v14
	v_rndne_f32_e32 v16, v14
	v_fmac_f32_e32 v15, 0xb2a5705f, v7
	v_sub_f32_e32 v14, v14, v16
	v_add_f32_e32 v14, v14, v15
	v_cvt_i32_f32_e32 v16, v16
	v_exp_f32_e32 v14, v14
	v_cmp_nlt_f32_e32 vcc, s22, v7
	s_nop 0
	v_ldexp_f32 v14, v14, v16
	v_cndmask_b32_e32 v14, 0, v14, vcc
	v_cmp_ngt_f32_e32 vcc, s23, v7
	s_nop 1
	v_cndmask_b32_e32 v14, v162, v14, vcc
	v_add_f32_e32 v14, 1.0, v14
	v_div_scale_f32 v15, s[8:9], v14, v14, v7
	v_rcp_f32_e32 v16, v15
	v_div_scale_f32 v17, vcc, v7, v14, v7
	v_fma_f32 v18, -v15, v16, 1.0
	v_fmac_f32_e32 v16, v18, v16
	v_mul_f32_e32 v18, v17, v16
	v_fma_f32 v19, -v15, v18, v17
	v_fmac_f32_e32 v18, v19, v16
	v_fma_f32 v15, -v15, v18, v17
	v_div_fmas_f32 v15, v15, v16, v18
	v_div_fixup_f32 v7, v15, v14, v7
	ds_write_b32 v0, v7 offset:5120
	s_waitcnt vmcnt(5)
	v_mul_f32_e32 v14, 0xbfb8aa3b, v8
	v_fma_f32 v15, v8, s30, -v14
	v_rndne_f32_e32 v16, v14
	v_fmac_f32_e32 v15, 0xb2a5705f, v8
	v_sub_f32_e32 v14, v14, v16
	v_add_f32_e32 v14, v14, v15
	v_cvt_i32_f32_e32 v16, v16
	v_exp_f32_e32 v14, v14
	v_cmp_nlt_f32_e32 vcc, s22, v8
	s_nop 0
	v_ldexp_f32 v14, v14, v16
	v_cndmask_b32_e32 v14, 0, v14, vcc
	v_cmp_ngt_f32_e32 vcc, s23, v8
	s_nop 1
	v_cndmask_b32_e32 v14, v162, v14, vcc
	v_add_f32_e32 v14, 1.0, v14
	v_div_scale_f32 v15, s[8:9], v14, v14, v8
	v_rcp_f32_e32 v16, v15
	v_div_scale_f32 v17, vcc, v8, v14, v8
	v_fma_f32 v18, -v15, v16, 1.0
	v_fmac_f32_e32 v16, v18, v16
	v_mul_f32_e32 v18, v17, v16
	v_fma_f32 v19, -v15, v18, v17
	v_fmac_f32_e32 v18, v19, v16
	v_fma_f32 v15, -v15, v18, v17
	v_div_fmas_f32 v15, v15, v16, v18
	v_div_fixup_f32 v8, v15, v14, v8
	ds_write_b32 v0, v8 offset:6144
	s_waitcnt vmcnt(4)
	v_mul_f32_e32 v14, 0xbfb8aa3b, v9
	v_fma_f32 v15, v9, s30, -v14
	v_rndne_f32_e32 v16, v14
	v_fmac_f32_e32 v15, 0xb2a5705f, v9
	v_sub_f32_e32 v14, v14, v16
	v_add_f32_e32 v14, v14, v15
	v_cvt_i32_f32_e32 v16, v16
	v_exp_f32_e32 v14, v14
	v_cmp_nlt_f32_e32 vcc, s22, v9
	s_nop 0
	v_ldexp_f32 v14, v14, v16
	v_cndmask_b32_e32 v14, 0, v14, vcc
	v_cmp_ngt_f32_e32 vcc, s23, v9
	s_nop 1
	v_cndmask_b32_e32 v14, v162, v14, vcc
	v_add_f32_e32 v14, 1.0, v14
	v_div_scale_f32 v15, s[8:9], v14, v14, v9
	v_rcp_f32_e32 v16, v15
	v_div_scale_f32 v17, vcc, v9, v14, v9
	v_fma_f32 v18, -v15, v16, 1.0
	v_fmac_f32_e32 v16, v18, v16
	v_mul_f32_e32 v18, v17, v16
	v_fma_f32 v19, -v15, v18, v17
	v_fmac_f32_e32 v18, v19, v16
	v_fma_f32 v15, -v15, v18, v17
	v_div_fmas_f32 v15, v15, v16, v18
	v_div_fixup_f32 v9, v15, v14, v9
	ds_write_b32 v0, v9 offset:7168
	s_waitcnt vmcnt(3)
	v_mul_f32_e32 v14, 0xbfb8aa3b, v10
	v_fma_f32 v15, v10, s30, -v14
	v_rndne_f32_e32 v16, v14
	v_fmac_f32_e32 v15, 0xb2a5705f, v10
	v_sub_f32_e32 v14, v14, v16
	v_add_f32_e32 v14, v14, v15
	v_cvt_i32_f32_e32 v16, v16
	v_exp_f32_e32 v14, v14
	v_cmp_nlt_f32_e32 vcc, s22, v10
	s_nop 0
	v_ldexp_f32 v14, v14, v16
	v_cndmask_b32_e32 v14, 0, v14, vcc
	v_cmp_ngt_f32_e32 vcc, s23, v10
	s_nop 1
	v_cndmask_b32_e32 v14, v162, v14, vcc
	v_add_f32_e32 v14, 1.0, v14
	v_div_scale_f32 v15, s[8:9], v14, v14, v10
	v_rcp_f32_e32 v16, v15
	v_div_scale_f32 v17, vcc, v10, v14, v10
	v_fma_f32 v18, -v15, v16, 1.0
	v_fmac_f32_e32 v16, v18, v16
	v_mul_f32_e32 v18, v17, v16
	v_fma_f32 v19, -v15, v18, v17
	v_fmac_f32_e32 v18, v19, v16
	v_fma_f32 v15, -v15, v18, v17
	v_div_fmas_f32 v15, v15, v16, v18
	v_div_fixup_f32 v10, v15, v14, v10
	ds_write_b32 v0, v10 offset:8192
	s_waitcnt vmcnt(2)
	v_mul_f32_e32 v14, 0xbfb8aa3b, v11
	v_fma_f32 v15, v11, s30, -v14
	v_rndne_f32_e32 v16, v14
	v_fmac_f32_e32 v15, 0xb2a5705f, v11
	v_sub_f32_e32 v14, v14, v16
	v_add_f32_e32 v14, v14, v15
	v_cvt_i32_f32_e32 v16, v16
	v_exp_f32_e32 v14, v14
	v_cmp_nlt_f32_e32 vcc, s22, v11
	s_nop 0
	v_ldexp_f32 v14, v14, v16
	v_cndmask_b32_e32 v14, 0, v14, vcc
	v_cmp_ngt_f32_e32 vcc, s23, v11
	s_nop 1
	v_cndmask_b32_e32 v14, v162, v14, vcc
	v_add_f32_e32 v14, 1.0, v14
	v_div_scale_f32 v15, s[8:9], v14, v14, v11
	v_rcp_f32_e32 v16, v15
	v_div_scale_f32 v17, vcc, v11, v14, v11
	v_fma_f32 v18, -v15, v16, 1.0
	v_fmac_f32_e32 v16, v18, v16
	v_mul_f32_e32 v18, v17, v16
	v_fma_f32 v19, -v15, v18, v17
	v_fmac_f32_e32 v18, v19, v16
	v_fma_f32 v15, -v15, v18, v17
	v_div_fmas_f32 v15, v15, v16, v18
	v_div_fixup_f32 v11, v15, v14, v11
	ds_write_b32 v0, v11 offset:9216
	s_waitcnt vmcnt(1)
	v_mul_f32_e32 v14, 0xbfb8aa3b, v12
	v_fma_f32 v15, v12, s30, -v14
	v_rndne_f32_e32 v16, v14
	v_fmac_f32_e32 v15, 0xb2a5705f, v12
	v_sub_f32_e32 v14, v14, v16
	v_add_f32_e32 v14, v14, v15
	v_cvt_i32_f32_e32 v16, v16
	v_exp_f32_e32 v14, v14
	v_cmp_nlt_f32_e32 vcc, s22, v12
	s_nop 0
	v_ldexp_f32 v14, v14, v16
	v_cndmask_b32_e32 v14, 0, v14, vcc
	v_cmp_ngt_f32_e32 vcc, s23, v12
	s_nop 1
	v_cndmask_b32_e32 v14, v162, v14, vcc
	v_add_f32_e32 v14, 1.0, v14
	v_div_scale_f32 v15, s[8:9], v14, v14, v12
	v_rcp_f32_e32 v16, v15
	v_div_scale_f32 v17, vcc, v12, v14, v12
	v_fma_f32 v18, -v15, v16, 1.0
	v_fmac_f32_e32 v16, v18, v16
	v_mul_f32_e32 v18, v17, v16
	v_fma_f32 v19, -v15, v18, v17
	v_fmac_f32_e32 v18, v19, v16
	v_fma_f32 v15, -v15, v18, v17
	v_div_fmas_f32 v15, v15, v16, v18
	v_div_fixup_f32 v12, v15, v14, v12
	ds_write_b32 v0, v12 offset:10240
	s_waitcnt vmcnt(0)
	v_mul_f32_e32 v14, 0xbfb8aa3b, v13
	v_fma_f32 v15, v13, s30, -v14
	v_rndne_f32_e32 v16, v14
	v_fmac_f32_e32 v15, 0xb2a5705f, v13
	v_sub_f32_e32 v14, v14, v16
	v_add_f32_e32 v14, v14, v15
	v_cvt_i32_f32_e32 v16, v16
	v_exp_f32_e32 v14, v14
	v_cmp_nlt_f32_e32 vcc, s22, v13
	s_nop 0
	v_ldexp_f32 v14, v14, v16
	v_cndmask_b32_e32 v14, 0, v14, vcc
	v_cmp_ngt_f32_e32 vcc, s23, v13
	s_nop 1
	v_cndmask_b32_e32 v14, v162, v14, vcc
	v_add_f32_e32 v14, 1.0, v14
	v_div_scale_f32 v15, s[8:9], v14, v14, v13
	v_rcp_f32_e32 v16, v15
	v_div_scale_f32 v17, vcc, v13, v14, v13
	v_fma_f32 v18, -v15, v16, 1.0
	v_fmac_f32_e32 v16, v18, v16
	v_mul_f32_e32 v18, v17, v16
	v_fma_f32 v19, -v15, v18, v17
	v_fmac_f32_e32 v18, v19, v16
	v_fma_f32 v15, -v15, v18, v17
	v_div_fmas_f32 v15, v15, v16, v18
	v_div_fixup_f32 v13, v15, v14, v13
	ds_write_b32 v0, v13 offset:11264
	s_or_b64 exec, exec, s[4:5]
	s_lshl_b32 s2, s1, 1
	s_add_i32 s3, s2, s65
	s_mul_hi_i32 s2, s3, 0x2aaaaaab
	s_lshr_b32 s4, s2, 31
	s_ashr_i32 s2, s2, 5
	s_add_i32 s2, s2, s4
	s_mul_i32 s4, s2, 0xc0
	s_waitcnt lgkmcnt(0)
	s_barrier
	s_load_dwordx2 s[6:7], s[54:55], 0x20
	s_sub_i32 s3, s3, s4
	v_bfe_u32 v0, v38, 3, 5
	s_lshl_b32 s4, s3, 5
	v_mul_hi_u32_u24_e32 v1, 0xc0000, v0
	v_mul_u32_u24_e32 v0, 0xc0000, v0
	v_mov_b32_e32 v2, 0x1800000
	s_ashr_i32 s5, s4, 31
	v_mad_i64_i32 v[0:1], s[8:9], s2, v2, v[0:1]
	s_lshl_b64 s[8:9], s[4:5], 2
	v_and_b32_e32 v2, 7, v38
	s_waitcnt lgkmcnt(0)
	s_add_u32 s6, s6, s8
	v_lshrrev_b32_e32 v41, 3, v39
	v_lshl_or_b32 v0, v2, 4, v0
	s_addc_u32 s7, s7, s9
	v_mov_b32_e32 v24, 0
	v_lshl_add_u64 v[36:37], s[6:7], 0, v[0:1]
	v_lshl_add_u32 v42, v41, 7, s33
	s_mov_b64 s[6:7], 0
	v_mov_b32_e32 v25, v24
	v_mov_b32_e32 v26, v24
	v_mov_b32_e32 v27, v24
	v_mov_b32_e32 v32, v24
	v_mov_b32_e32 v33, v24
	v_mov_b32_e32 v34, v24
	v_mov_b32_e32 v35, v24
	v_mov_b32_e32 v28, v24
	v_mov_b32_e32 v29, v24
	v_mov_b32_e32 v30, v24
	v_mov_b32_e32 v31, v24
